# neighbourhood attention START uses the fixed shift (QK-norm bound + max of the head's bias table), steady loops unchanged
# baseline (speedup 1.0000x reference)
;   #define WB(a,b) do{ if constexpr(DV2){WAIT_BAR(b);} else {WAIT_BAR(a);} }while(0)
;   #define DMA_K(t,slot) glds16(ksrc+(long)TMAP(t)*KVBLK*PQ,(unsigned)__builtin_amdgcn_readfirstlane(kdst+(slot)))
;   #define DMA_V(t,slot) glds16(vsrc+(long)TMAP(t)*KVBLK*PQ,(unsigned)__builtin_amdgcn_readfirstlane(vdst+(slot)))
;   #define DMA_V2(t,slot) do{ if constexpr(DV2) glds16(v2src+(long)TMAP(t)*KVBLK*PQ,(unsigned)__builtin_amdgcn_readfirstlane(v2dst+(slot))); }while(0)
;     ...
;   int tid=threadIdx.x; asm volatile("":"+v"(tid)); const int lane=tid&63,r32=lane&31,hi=lane>>5; const int wid=__builtin_amdgcn_readfirstlane(tid>>6);
;   const bf16*Qw=Qu+(long)wid*QBLK*PQ;
;   const unsigned lds0=(unsigned)(uintptr_t)shm;
;   float*wsf=(float*)(shm+LDS_WS)+wid*64;
;   const bf16*ksrc=Kh+(long)lane*PQ+wid*8;
;   const bf16*vsrc=Vh+(long)(16*(wid&3)+(lane>>2))*PQ+(wid>>2)*32+(lane&3)*8;
;   const unsigned kdst=lds0+LDS_K+wid*1024, vdst=lds0+LDS_V+wid*1024;
;     ...
;   const bf16*v2src=DV2?V2h+(vsrc-Vh):vsrc; const unsigned v2dst=lds0+LDS_V2+wid*1024;
;     ...
;   const int vb0=(int)(lds0+LDS_V)+((lane>>4)&1)*32+(lane&3)*8+(4*hi+((lane&15)>>2))*64;
;   const char*Kbase=shm+LDS_K; bf16x8 kf[8];
;   const lds_cptr shm3=(lds_cptr)shm; const lds_cptr kp0=shm3+LDS_K+hi*1024+r32*16; const lds_cptr vp0=shm3+LDS_V+((lane>>4)&1)*32+(lane&3)*8+(4*hi+((lane&15)>>2))*64;
;   DMA_K(0,0);DMA_V(0,0);DMA_V2(0,0);DMA_K(1,SLOTB);
;   bf16x8 qr[4];
;   #pragma unroll
;   for(int d0=0;d0<4;++d0)qr[d0]=*reinterpret_cast<const bf16x8*>(&Qw[(long)r32*PQ+d0*16+hi*8]);
;   float mhat=0.f,l_reg=0.f;f32x16 o[ND];
;   #pragma unroll
;   for(int d_=0;d_<ND;++d_)o[d_]=f32x16{};
;   f32x16 negm=f32x16{}; if constexpr(!DV2) asm volatile("":"+v"(negm));
;   const f32x16 zero16=f32x16{};
;     ...
;   const int nq_r=qrow0+(wid>>1), nq_c=(wid&1)*32+r32, n_rsw=min(max(nq_r-4,0),56), n_cs=min(max(nq_c-8,0),48);
;     ...
;   bool resc=false;
;     ...
;   f32x16 pA0,pA1,pB0,pB1;
;   int sl_prev=0,sl_cur=0,sl_next=SLOTB;
;     ...
;   DMA_K(2,2*SLOTB);
;   WB(3,4);
;   qkt(pA0,pA1,Kbase,qr,NEGM,r32,hi);asm volatile("s_nop 15\n\ts_nop 7":"+v"(pA0),"+v"(pA1));CMASK(pA0,pA1,0);
.LBB0_350:
	s_or_b64 exec, exec, s[4:5]
	s_lshl_b32 s4, s36, 2
	v_writelane_b32 v255, s36, 9
	v_sub_u32_e64 v0, s4, 4 clamp
	s_and_b32 s11, s33, 15
	v_mov_b32_e32 v12, v234
	v_writelane_b32 v255, s4, 10
	v_readfirstlane_b32 s4, v0
	s_lshl_b32 s5, s11, 2
	s_min_u32 s4, s4, 52
	v_readfirstlane_b32 s14, v12
	v_sub_u32_e64 v0, s5, 4 clamp
	s_ashr_i32 s74, s14, 6
	v_writelane_b32 v255, s4, 11
	v_readfirstlane_b32 s4, v0
	s_ashr_i32 s75, s74, 31
	v_writelane_b32 v255, s33, 12
	s_min_u32 s8, s4, 52
	s_lshl_b64 s[6:7], s[74:75], 12
	v_and_b32_e32 v202, 63, v12
	v_writelane_b32 v255, s34, 13
	s_add_u32 s6, s34, s6
	v_writelane_b32 v255, s35, 14
	s_addc_u32 s7, s35, s7
	v_lshlrev_b32_e32 v2, 7, v202
	v_mov_b32_e32 v3, v1
	s_lshl_b32 s12, s74, 3
	s_lshl_b32 s4, s74, 4
	v_bfe_u32 v4, v12, 2, 4
	v_writelane_b32 v255, s90, 15
	s_ashr_i32 s13, s12, 31
	v_and_or_b32 v4, s4, 48, v4
	v_lshl_add_u64 v[2:3], s[90:91], 0, v[2:3]
	s_ashr_i32 s4, s14, 3
	v_lshl_add_u64 v[2:3], s[12:13], 1, v[2:3]
	s_and_b32 s12, s4, 0xffffffe0
	s_and_b32 s10, s14, 0x3fffffc0
	s_ashr_i32 s13, s12, 31
	s_lshl_b32 s4, s74, 10
	v_writelane_b32 v255, s91, 16
	v_lshlrev_b32_e32 v4, 7, v4
	v_mov_b32_e32 v5, v1
	v_lshlrev_b32_e32 v203, 3, v12
	s_cmp_lg_u32 0, -1
	v_writelane_b32 v255, s88, 17
	v_and_b32_e32 v206, 24, v203
	s_cselect_b32 s9, 0, 0
	v_lshl_add_u64 v[4:5], s[88:89], 0, v[4:5]
	v_bfe_u32 v205, v12, 5, 1
	v_lshl_add_u64 v[4:5], s[12:13], 1, v[4:5]
	v_lshlrev_b32_e32 v6, 1, v206
	v_mov_b32_e32 v7, v1
	s_add_i32 s33, s4, s9
	s_mov_b32 s4, m0
	s_mov_b32 m0, s33
	s_nop 0
	global_load_lds_dwordx4 v[2:3], off
	s_mov_b32 m0, s4
	v_and_b32_e32 v204, 31, v12
	v_writelane_b32 v255, s89, 18
	v_lshl_add_u64 v[14:15], v[4:5], 0, v[6:7]
	s_add_i32 s88, s33, 0x6000
	s_mov_b32 s4, m0
	s_mov_b32 m0, s88
	s_nop 0
	global_load_lds_dwordx4 v[14:15], off
	s_mov_b32 m0, s4
	v_lshl_add_u64 v[4:5], v[2:3], 0, s[86:87]
	v_lshlrev_b32_e32 v209, 4, v205
	s_add_i32 s4, s33, 0x2000
	s_mov_b32 s9, m0
	s_mov_b32 m0, s4
	s_nop 0
	global_load_lds_dwordx4 v[4:5], off
	s_mov_b32 m0, s9
	v_lshl_or_b32 v4, v204, 7, v209
	global_load_dwordx4 v[176:179], v4, s[6:7]
	global_load_dwordx4 v[172:175], v4, s[6:7] offset:32
	global_load_dwordx4 v[168:171], v4, s[6:7] offset:64
	global_load_dwordx4 v[164:167], v4, s[6:7] offset:96
	v_mov_b32_e32 v48, v1
	v_mov_b32_e32 v49, v1
	v_mov_b32_e32 v50, v1
	v_mov_b32_e32 v51, v1
	v_mov_b32_e32 v52, v1
	v_mov_b32_e32 v53, v1
	v_mov_b32_e32 v54, v1
	v_mov_b32_e32 v55, v1
	v_mov_b32_e32 v56, v1
	v_mov_b32_e32 v57, v1
	v_mov_b32_e32 v58, v1
	v_mov_b32_e32 v59, v1
	v_mov_b32_e32 v60, v1
	v_mov_b32_e32 v61, v1
	v_mov_b32_e32 v62, v1
	v_mov_b32_e32 v63, v1
	v_lshlrev_b32_e32 v4, 10, v205
	v_lshlrev_b32_e32 v5, 4, v204
	v_add3_u32 v215, 0, v4, v5
	v_lshl_add_u64 v[4:5], v[2:3], 0, s[96:97]
	s_add_i32 s4, s33, 0x4000
	s_mov_b32 s6, m0
	s_mov_b32 m0, s4
	s_nop 0
	global_load_lds_dwordx4 v[4:5], off
	s_mov_b32 m0, s6
	s_waitcnt vmcnt(3) lgkmcnt(0)
	s_barrier
	v_and_b32_e32 v20, 63, v234
	v_min_u32_e32 v21, 16, v20
	v_lshlrev_b32_e32 v20, 2, v20
	v_lshlrev_b32_e32 v21, 2, v21
	v_add_u32_e32 v20, 0x16800, v20
	v_add_u32_e32 v21, 0x16f00, v21
	ds_read_b32 v22, v20
	ds_read_b32 v23, v20 offset:256
	ds_read_b32 v24, v20 offset:512
	ds_read_b32 v25, v20 offset:768
	ds_read_b32 v26, v20 offset:1024
	ds_read_b32 v27, v20 offset:1280
	ds_read_b32 v28, v20 offset:1536
	ds_read_b32 v29, v21
	s_waitcnt lgkmcnt(0)
	v_max3_f32 v22, |v22|, |v23|, |v24|
	v_max3_f32 v22, v22, |v25|, |v26|
	v_max3_f32 v22, v22, |v27|, |v28|
	v_max_f32_e64 v22, v22, |v29|
	s_nop 1
	v_max_f32_dpp v22, v22, v22 quad_perm:[1,0,3,2] row_mask:0xf bank_mask:0xf
	s_nop 1
	v_max_f32_dpp v22, v22, v22 quad_perm:[2,3,0,1] row_mask:0xf bank_mask:0xf
	s_nop 1
	v_max_f32_dpp v22, v22, v22 row_half_mirror row_mask:0xf bank_mask:0xf
	s_nop 1
	v_max_f32_dpp v22, v22, v22 row_mirror row_mask:0xf bank_mask:0xf
	s_nop 1
	v_readlane_b32 s12, v22, 0
	v_readlane_b32 s13, v22, 16
	v_readlane_b32 s16, v22, 32
	v_readlane_b32 s17, v22, 48
	s_max_u32 s12, s12, s13
	s_max_u32 s16, s16, s17
	s_max_u32 s12, s12, s16
	v_readlane_b32 s99, v255, 40
	v_mov_b32_e32 v23, s12
	v_add_f32_e32 v23, s99, v23
	s_nop 1
	v_readfirstlane_b32 s12, v23
	s_cmp_gt_u32 s12, 0x42200000
	s_cselect_b32 s12, 0, s12
	s_cmp_eq_u32 s99, 0
	s_cselect_b32 s12, 0, s12
	s_nop 3
	v_writelane_b32 v255, s12, 43
	ds_read_b128 v[4:7], v215
	ds_read_b128 v[8:11], v215 offset:512
	s_mul_i32 s6, s11, 0x1f0
	s_lshl_b32 s11, s74, 5
	v_and_or_b32 v214, s11, 32, v204
	s_waitcnt vmcnt(3) lgkmcnt(1)
	v_mfma_f32_32x32x16_bf16 v[64:79], v[4:7], v[176:179], v[48:63]
	ds_read_b128 v[4:7], v215 offset:2048
	s_lshl_b32 s10, s10, 2
	s_add_i32 s85, s10, 0
	v_lshlrev_b32_e32 v217, 2, v205
	s_ashr_i32 s89, s14, 7
	s_mul_i32 s7, s8, 0x7c
	v_cmp_gt_u32_e32 vcc, 52, v0
	s_waitcnt lgkmcnt(1)
	v_mfma_f32_32x32x16_bf16 v[48:63], v[8:11], v[176:179], v[48:63]
	ds_read_b128 v[8:11], v215 offset:2560
	s_add_i32 s5, s89, s5
	v_cndmask_b32_e32 v0, 52, v0, vcc
	s_max_i32 s5, s5, 4
	v_lshlrev_b32_e32 v0, 13, v0
	v_mov_b32_e32 v46, v1
	v_mov_b32_e32 v47, v1
	s_waitcnt vmcnt(2) lgkmcnt(1)
	v_mfma_f32_32x32x16_bf16 v[64:79], v[4:7], v[172:175], v[64:79]
	ds_read_b128 v[4:7], v215 offset:4608
	ds_read_b128 v[18:21], v215 offset:4096
	s_add_i32 s5, s5, -4
	v_mov_b32_e32 v32, v1
	v_mov_b32_e32 v33, v1
	v_mov_b32_e32 v34, v1
	v_mov_b32_e32 v35, v1
	v_mov_b32_e32 v36, v1
	s_waitcnt lgkmcnt(2)
	v_mfma_f32_32x32x16_bf16 v[48:63], v[8:11], v[172:175], v[48:63]
	v_lshlrev_b32_e32 v8, 1, v12
	v_lshlrev_b32_e32 v9, 4, v12
	v_and_b32_e32 v207, 32, v8
	v_and_b32_e32 v8, 0xc0, v9
	v_lshl_or_b32 v208, v205, 8, v8
	v_mov_b32_e32 v37, v1
	v_add_u32_e32 v12, 0, v207
	s_waitcnt vmcnt(1) lgkmcnt(0)
; __device__ __forceinline__ float max3f(float a,float b,float c){float r;asm("v_max3_f32 %0, %1, %2, %3":"=v"(r):"v"(a),"v"(b),"v"(c));return r;}
; __device__ __forceinline__ float max2f(float a,float b){float r;asm("v_max_f32_e32 %0, %1, %2":"=v"(r):"v"(a),"v"(b));return r;}
; __device__ __forceinline__ float rowmax(const f32x16&p0,const f32x16&p1){
;   float a=max3f(p0[0],p0[1],p1[0]),b=max3f(p0[2],p0[3],p1[1]);a=max3f(a,p1[2],p1[3]);
;   #pragma unroll
;   for(int r=4;r<16;r+=4){a=max3f(a,p0[r],p0[r+1]);b=max3f(b,p0[r+2],p0[r+3]);a=max3f(a,p1[r],p1[r+1]);b=max3f(b,p1[r+2],p1[r+3]);}
;   const float m=max2f(a,b);
;   auto rr=__builtin_amdgcn_permlane32_swap(__float_as_uint(m),__float_as_uint(m),false,false);
;   return max2f(__uint_as_float(rr[0]),__uint_as_float(rr[1]));
; }
;     ...
;   qkt(pA0,pA1,Kbase,qr,NEGM,r32,hi);asm volatile("s_nop 15\n\ts_nop 7":"+v"(pA0),"+v"(pA1));CMASK(pA0,pA1,0);
;   START(pA0,pA1);
	v_mfma_f32_32x32x16_bf16 v[64:79], v[18:21], v[168:171], v[64:79]
	ds_read_b128 v[8:11], v215 offset:6656
	ds_read_b128 v[18:21], v215 offset:6144
	v_mov_b32_e32 v38, v1
	v_mov_b32_e32 v39, v1
	v_mov_b32_e32 v40, v1
	v_mov_b32_e32 v41, v1
	v_mov_b32_e32 v42, v1
	v_mov_b32_e32 v43, v1
	v_mfma_f32_32x32x16_bf16 v[48:63], v[4:7], v[168:171], v[48:63]
	v_sub_u32_e64 v4, v214, 8 clamp
	v_mov_b32_e32 v44, v1
	v_mov_b32_e32 v45, v1
	v_lshl_add_u64 v[188:189], v[2:3], 0, v[0:1]
	s_min_u32 s5, s5, 56
	s_mov_b32 s9, 3
	s_mov_b32 s4, 0
	s_waitcnt vmcnt(0) lgkmcnt(0)
	v_mfma_f32_32x32x16_bf16 v[64:79], v[18:21], v[164:167], v[64:79]
	s_movk_i32 s93, 0x2000
	s_movk_i32 s91, 0x4000
	v_add3_u32 v216, v12, v206, v208
	v_lshl_add_u64 v[190:191], v[188:189], 0, s[80:81]
	s_sub_i32 s90, s8, s5
	v_mov_b32_e32 v218, 0
	v_mfma_f32_32x32x16_bf16 v[48:63], v[8:11], v[164:167], v[48:63]
	s_nop 15
	s_nop 7
	s_nop 0
	v_max3_f32 v5, v64, v65, v48
	v_max3_f32 v6, v66, v67, v49
	s_nop 0
	v_max3_f32 v5, v5, v50, v51
	v_max3_f32 v6, v6, v70, v71
	s_nop 0
	v_max3_f32 v5, v5, v68, v69
	v_max3_f32 v6, v6, v54, v55
	s_nop 0
	v_max3_f32 v5, v5, v52, v53
	v_max3_f32 v6, v6, v74, v75
	s_nop 0
	v_max3_f32 v5, v5, v72, v73
	v_max3_f32 v6, v6, v58, v59
	s_nop 0
	v_max3_f32 v5, v5, v56, v57
	v_max3_f32 v6, v6, v78, v79
	s_nop 0
	v_max3_f32 v5, v5, v76, v77
	v_max3_f32 v6, v6, v62, v63
	s_nop 0
	v_max3_f32 v5, v5, v60, v61
	s_nop 0
	v_max_f32_e32 v5, v5, v6
	s_nop 0
	v_mov_b32_e32 v6, v5
	s_nop 1
	v_permlane32_swap_b32_e32 v5, v6
	v_max_f32_e32 v5, v5, v6
	v_readlane_b32 s99, v255, 43
	s_cmp_eq_u32 s99, 0
	s_cbranch_scc1 .Lfsk1_start_gen
	v_mov_b32_e32 v5, s99
; #define WAIT_BAR(N) asm volatile("s_waitcnt vmcnt(" #N ") lgkmcnt(0)\n\ts_barrier":::"memory")
;   #define WB(a,b) do{ if constexpr(DV2){WAIT_BAR(b);} else {WAIT_BAR(a);} }while(0)
;   #define DMA_K(t,slot) glds16(ksrc+(long)TMAP(t)*KVBLK*PQ,(unsigned)__builtin_amdgcn_readfirstlane(kdst+(slot)))
;   #define DMA_V(t,slot) glds16(vsrc+(long)TMAP(t)*KVBLK*PQ,(unsigned)__builtin_amdgcn_readfirstlane(vdst+(slot)))
;   #define DMA_V2(t,slot) do{ if constexpr(DV2) glds16(v2src+(long)TMAP(t)*KVBLK*PQ,(unsigned)__builtin_amdgcn_readfirstlane(v2dst+(slot))); }while(0)
;   #define ROT() do{sl_prev=sl_cur;sl_cur=sl_next;sl_next=(sl_next==(NSLOT-1)*SLOTB)?0:sl_next+SLOTB;}while(0)
;     ...
;   const int nq_r=qrow0+(wid>>1), nq_c=(wid&1)*32+r32, n_rsw=min(max(nq_r-4,0),56), n_cs=min(max(nq_c-8,0),48);
;     ...
;   bool resc=false;
;     ...
;   f32x16 pA0,pA1,pB0,pB1;
;   int sl_prev=0,sl_cur=0,sl_next=SLOTB;
;     ...
;   DMA_K(2,2*SLOTB);
;   WB(3,4);
;   qkt(pA0,pA1,Kbase,qr,NEGM,r32,hi);asm volatile("s_nop 15\n\ts_nop 7":"+v"(pA0),"+v"(pA1));CMASK(pA0,pA1,0);
;   START(pA0,pA1);
;   _Pragma("unroll") for(int r=0;r<16;++r)pA1[r]=__builtin_amdgcn_exp2f(pA1[r]);
;   WAIT_BAR(0);
;   DMA_K(3,0);DMA_V(1,SLOTB);DMA_V2(1,SLOTB);
;   ROT();
;   kload8(kf,kp0+sl_cur);
;   WB(2,3);
.Lfsk1_start_gen:
	s_nop 0
	v_add_f32_e32 v213, v1, v5
	v_sub_f32_e32 v6, v64, v5
	v_sub_f32_e32 v7, v48, v5
	v_sub_f32_e32 v8, v65, v5
	v_sub_f32_e32 v9, v49, v5
	v_sub_f32_e32 v10, v66, v5
	s_nop 0
	v_xor_b32_e32 v64, 0x80000000, v213
	v_sub_f32_e32 v11, v50, v5
	v_sub_f32_e32 v13, v67, v5
	v_sub_f32_e32 v17, v51, v5
	v_sub_f32_e32 v18, v68, v5
	v_sub_f32_e32 v19, v52, v5
	v_sub_f32_e32 v20, v69, v5
	v_sub_f32_e32 v21, v53, v5
	v_sub_f32_e32 v22, v70, v5
	v_sub_f32_e32 v23, v54, v5
	v_sub_f32_e32 v24, v71, v5
	v_sub_f32_e32 v25, v55, v5
	v_sub_f32_e32 v26, v72, v5
	v_sub_f32_e32 v27, v56, v5
	v_sub_f32_e32 v28, v73, v5
	v_sub_f32_e32 v29, v57, v5
	v_sub_f32_e32 v30, v74, v5
	v_sub_f32_e32 v31, v58, v5
	v_sub_f32_e32 v48, v75, v5
	v_sub_f32_e32 v49, v59, v5
	v_sub_f32_e32 v50, v76, v5
	v_sub_f32_e32 v51, v60, v5
	v_sub_f32_e32 v52, v77, v5
	v_sub_f32_e32 v53, v61, v5
	v_sub_f32_e32 v54, v78, v5
	v_sub_f32_e32 v55, v62, v5
	v_sub_f32_e32 v56, v79, v5
	v_sub_f32_e32 v5, v63, v5
	v_mov_b32_e32 v65, v64
	v_mov_b32_e32 v66, v64
	v_mov_b32_e32 v67, v64
	v_mov_b32_e32 v68, v64
	v_mov_b32_e32 v69, v64
	v_mov_b32_e32 v70, v64
	v_mov_b32_e32 v71, v64
	v_mov_b32_e32 v72, v64
	v_mov_b32_e32 v73, v64
	v_mov_b32_e32 v74, v64
	v_mov_b32_e32 v75, v64
	v_mov_b32_e32 v76, v64
	v_mov_b32_e32 v77, v64
	v_mov_b32_e32 v78, v64
	v_mov_b32_e32 v79, v64
	v_exp_f32_e32 v96, v6
	v_exp_f32_e32 v95, v5
	v_min_u32_e32 v6, 48, v4
	s_waitcnt vmcnt(0) lgkmcnt(0)
	s_barrier
	v_lshl_add_u64 v[4:5], v[2:3], 0, s[0:1]
	s_mov_b32 s10, m0
	s_mov_b32 m0, s33
	s_nop 0
	global_load_lds_dwordx4 v[4:5], off
	s_mov_b32 m0, s10
	v_lshl_add_u64 v[4:5], v[14:15], 0, s[86:87]
	s_add_i32 s10, s33, 0x8000
	s_mov_b32 s11, m0
	s_mov_b32 m0, s10
	s_nop 0
	global_load_lds_dwordx4 v[4:5], off
	s_mov_b32 m0, s11
	v_sub_u32_e32 v5, v217, v6
	v_cmp_gt_u32_e64 s[12:13], 16, v5
	v_or_b32_e32 v5, 32, v217
	v_sub_u32_e32 v5, v5, v6
	v_cmp_gt_u32_e64 s[14:15], 16, v5
	v_or_b32_e32 v5, 1, v217
	v_sub_u32_e32 v5, v5, v6
	v_cmp_gt_u32_e64 s[16:17], 16, v5
	v_or_b32_e32 v5, 33, v217
	v_sub_u32_e32 v5, v5, v6
	v_cmp_gt_u32_e64 s[18:19], 16, v5
	v_or_b32_e32 v5, 2, v217
	v_sub_u32_e32 v5, v5, v6
	v_cmp_gt_u32_e64 s[20:21], 16, v5
	v_or_b32_e32 v5, 34, v217
	v_sub_u32_e32 v5, v5, v6
	v_cmp_gt_u32_e64 s[22:23], 16, v5
	v_or_b32_e32 v5, 3, v217
	v_sub_u32_e32 v5, v5, v6
	v_cmp_gt_u32_e64 s[24:25], 16, v5
	v_or_b32_e32 v5, 35, v217
	v_sub_u32_e32 v5, v5, v6
	v_cmp_gt_u32_e64 s[26:27], 16, v5
	v_or_b32_e32 v5, 8, v217
	v_sub_u32_e32 v5, v5, v6
	v_cmp_gt_u32_e64 s[28:29], 16, v5
	v_or_b32_e32 v5, 40, v217
	v_sub_u32_e32 v5, v5, v6
	v_cmp_gt_u32_e64 s[30:31], 16, v5
	v_or_b32_e32 v5, 9, v217
	v_sub_u32_e32 v5, v5, v6
	v_cmp_gt_u32_e64 s[34:35], 16, v5
	v_or_b32_e32 v5, 41, v217
	v_sub_u32_e32 v5, v5, v6
	v_cmp_gt_u32_e64 s[36:37], 16, v5
	v_or_b32_e32 v5, 10, v217
	v_sub_u32_e32 v5, v5, v6
	v_cmp_gt_u32_e64 s[38:39], 16, v5
	v_or_b32_e32 v5, 42, v217
	v_sub_u32_e32 v5, v5, v6
	v_cmp_gt_u32_e64 s[40:41], 16, v5
	v_or_b32_e32 v5, 11, v217
	v_sub_u32_e32 v5, v5, v6
	v_cmp_gt_u32_e64 s[42:43], 16, v5
	v_or_b32_e32 v5, 43, v217
	v_sub_u32_e32 v5, v5, v6
	v_cmp_gt_u32_e64 s[44:45], 16, v5
	v_or_b32_e32 v5, 16, v217
	v_sub_u32_e32 v5, v5, v6
	v_cmp_gt_u32_e64 s[46:47], 16, v5
	v_or_b32_e32 v5, 48, v217
	v_sub_u32_e32 v5, v5, v6
	v_cmp_gt_u32_e64 s[48:49], 16, v5
	v_or_b32_e32 v5, 17, v217
	v_sub_u32_e32 v5, v5, v6
	v_cmp_gt_u32_e64 s[50:51], 16, v5
	v_or_b32_e32 v5, 49, v217
	v_sub_u32_e32 v5, v5, v6
	v_cmp_gt_u32_e64 s[52:53], 16, v5
	v_or_b32_e32 v5, 18, v217
	v_sub_u32_e32 v5, v5, v6
	v_cmp_gt_u32_e64 s[54:55], 16, v5
	v_or_b32_e32 v5, 50, v217
	v_sub_u32_e32 v5, v5, v6
	v_cmp_gt_u32_e64 s[56:57], 16, v5
	v_or_b32_e32 v5, 19, v217
	v_sub_u32_e32 v5, v5, v6
	v_cmp_gt_u32_e64 s[58:59], 16, v5
	v_or_b32_e32 v5, 51, v217
	v_sub_u32_e32 v5, v5, v6
	v_cmp_gt_u32_e64 s[60:61], 16, v5
	v_or_b32_e32 v5, 24, v217
	v_sub_u32_e32 v5, v5, v6
	v_cmp_gt_u32_e64 s[62:63], 16, v5
	v_or_b32_e32 v5, 56, v217
	v_sub_u32_e32 v5, v5, v6
	v_cmp_gt_u32_e64 s[64:65], 16, v5
	v_or_b32_e32 v5, 25, v217
	v_sub_u32_e32 v5, v5, v6
	v_exp_f32_e32 v100, v18
	v_exp_f32_e32 v101, v20
	v_exp_f32_e32 v102, v22
	v_exp_f32_e32 v103, v24
	v_exp_f32_e32 v104, v26
	v_exp_f32_e32 v105, v28
	v_exp_f32_e32 v84, v19
	v_exp_f32_e32 v85, v21
	v_exp_f32_e32 v86, v23
	v_exp_f32_e32 v87, v25
	v_exp_f32_e32 v88, v27
	v_exp_f32_e32 v89, v29
	ds_read_b128 v[180:183], v215 offset:8192
	ds_read_b128 v[156:159], v215 offset:8704
	ds_read_b128 v[152:155], v215 offset:10240
	ds_read_b128 v[148:151], v215 offset:10752
	ds_read_b128 v[144:147], v215 offset:12288
	ds_read_b128 v[26:29], v215 offset:12800
	ds_read_b128 v[22:25], v215 offset:14336
	ds_read_b128 v[18:21], v215 offset:14848
	v_cmp_gt_u32_e64 s[66:67], 16, v5
	v_or_b32_e32 v5, 57, v217
	v_sub_u32_e32 v5, v5, v6
	v_cmp_gt_u32_e64 s[68:69], 16, v5
	v_or_b32_e32 v5, 26, v217
	v_cmp_gt_u32_e64 s[10:11], 32, v202
	v_sub_u32_e32 v5, v5, v6
	v_exp_f32_e32 v80, v7
	v_writelane_b32 v255, s10, 19
	v_lshlrev_b32_e32 v4, 2, v204
	v_cmp_gt_u32_e64 s[70:71], 16, v5
	v_or_b32_e32 v5, 58, v217
	v_add_u32_e32 v7, s7, v209
	v_writelane_b32 v255, s11, 20
	v_add_u32_e32 v212, s85, v4
	v_sub_u32_e32 v5, v5, v6
	v_sub_u32_e32 v4, v7, v4
	s_mul_i32 s7, s89, 0x7c
	v_cmp_gt_u32_e64 s[72:73], 16, v5
	v_or_b32_e32 v5, 27, v217
	v_subrev_u32_e32 v4, s7, v4
	v_writelane_b32 v255, s74, 21
	s_lshl_b32 s7, s74, 7
	v_exp_f32_e32 v97, v8
	v_exp_f32_e32 v98, v10
	v_exp_f32_e32 v99, v13
	v_exp_f32_e32 v106, v30
	v_exp_f32_e32 v107, v48
	v_exp_f32_e32 v108, v50
	v_exp_f32_e32 v109, v52
	v_exp_f32_e32 v110, v54
	v_exp_f32_e32 v111, v56
	v_exp_f32_e32 v81, v9
	v_exp_f32_e32 v82, v11
	v_exp_f32_e32 v83, v17
	v_exp_f32_e32 v90, v31
	v_exp_f32_e32 v91, v49
	v_exp_f32_e32 v92, v51
	v_exp_f32_e32 v93, v53
	v_exp_f32_e32 v94, v55
	v_sub_u32_e32 v5, v5, v6
	s_and_b32 s7, s7, 0x80
	s_waitcnt vmcnt(2) lgkmcnt(0)
	s_barrier
	v_writelane_b32 v255, s75, 22
	v_subrev_u32_e32 v4, s7, v4
	v_cmp_gt_u32_e64 s[74:75], 16, v5
	v_or_b32_e32 v5, 59, v217
	v_sub_u32_e32 v5, v5, v6
	v_subrev_u32_e32 v192, s6, v4
	s_add_i32 s6, 0, 0x1622c
	v_mov_b64_e32 v[62:63], v[46:47]
	v_add_u32_e32 v193, s6, v192
	v_mov_b64_e32 v[60:61], v[44:45]
	v_mov_b64_e32 v[58:59], v[42:43]
	v_mov_b64_e32 v[56:57], v[40:41]
	v_mov_b64_e32 v[54:55], v[38:39]
	v_mov_b64_e32 v[52:53], v[36:37]
	v_mov_b64_e32 v[50:51], v[34:35]
	v_mov_b64_e32 v[48:49], v[32:33]
	v_cmp_gt_u32_e64 s[76:77], 16, v5
